# combo17 + attention units request the next work-queue ticket when leaving the k-tile loop (atomic round trip overlaps the unit's last tile and epilogue)
# speedup vs baseline: 1.0084x; 1.0004x over previous
; __global__ void __launch_bounds__(512, 2) fwd(Args a) {
;     ...
;                 for (;;) {
;                     if (tid_ == 0) MISC[16] = __hip_atomic_fetch_add(qh, 1u, __ATOMIC_RELAXED, __HIP_MEMORY_SCOPE_AGENT);
;                     __syncthreads();
;                     const int item = (int)MISC[16];
;                     __syncthreads();
;                     if (item >= Q_POST) break;
;                     int t2 = tid_; asm volatile("" : "+v"(t2)); const int l2 = t2 & 63, w2 = __builtin_amdgcn_readfirstlane(t2 >> 6);
;                     if (item < Q_PRE) { phase_pre(UB, UC, sb, l, in.lb_logits, in.gla_b + l * 512, item * 16 + w2, item * 16 + 16, 8, l2); item_publish(pre_cnt, t2); }
;                     else if (item < Q_PRE + 32) { const int id = item - Q_PRE; scan_unit(lds, UB, UC, sb, pre_cnt, Q_PRE, scan_cnt, 0, id >> 3, id & 7, 0, t2, w2, l2); }
;                     else if (item < Q_SCAN) { const int id = item - Q_PRE - 32; scan_unit(lds, UB, UC, sb, pre_cnt, Q_PRE, scan_cnt, 1, id >> 3, (id >> 1) & 3, id & 1, t2, w2, l2); }
.LBB0_498:
	s_or_b64 exec, exec, s[0:1]
	s_waitcnt vmcnt(0)
	v_mov_b32_e32 v0, s54
	s_waitcnt vmcnt(0) lgkmcnt(0)
	s_barrier
	ds_read_b32 v0, v0
	s_movk_i32 s0, 0x83f
	s_waitcnt lgkmcnt(0)
	s_barrier
	v_cmp_lt_i32_e32 vcc, s0, v0
	v_readfirstlane_b32 s56, v0
	s_mov_b64 s[0:1], -1
	s_cbranch_vccnz .LBB0_493
	v_mov_b32_e32 v213, 0
	v_mov_b32_e32 v186, v214
	s_nop 0
	v_readfirstlane_b32 s6, v186
	s_ashr_i32 s57, s6, 6
	v_and_b32_e32 v187, 63, v186
	s_cmpk_gt_i32 s56, 0x2ff
	s_cbranch_scc0 .LBB0_580
	s_cmpk_gt_u32 s56, 0x31f
	s_cbranch_scc0 .LBB0_559
	s_cmpk_gt_u32 s56, 0x33f
	s_cbranch_scc0 .LBB0_529
	s_cmpk_gt_u32 s56, 0x73f
	s_cbranch_scc0 .LBB0_517
	v_cmp_eq_u32_e32 vcc, 0, v186
	s_and_saveexec_b64 s[0:1], vcc
	s_cbranch_execz .LBB0_513
	s_mov_b32 s7, 0x400001
	s_branch .LBB0_506

; #define LAS __attribute__((address_space(3)))
; __device__ __forceinline__ void attn_unit(LAS unsigned char* lds, const bf16* UA, bf16* Y, int bl, int h, int qb,
;                                           const float* qkg, const float* rel_bias, const float* lamv, const float* dgain, float lam_init, int tid, int wave, int lane) {
;     ...
;     for (int kt = 0; kt < NT; ++kt) {
;         const int buf = kt & 1;
;         if (kt + 1 < NT) AT_LOAD(kt + 1);
;         if (kt <= qc) {
;             const bool far_ = (qc - kt) >= 3;
;             const LAS unsigned char* Kb = lds + AT_K + buf * AT_KBUF;
;             const LAS unsigned char* Vb = lds + AT_V + buf * AT_VBUF;
;             f32x4 S[4][2];
;             bf16x8 kf[4][2];
; #pragma unroll
;             for (int kb = 0; kb < 4; ++kb)
; #pragma unroll
;                 for (int ks = 0; ks < 2; ++ks) kf[kb][ks] = *(const LAS bf16x8*)(Kb + koff + (16 * kb) * AT_KROW + ks * 64);
;             __builtin_amdgcn_s_setprio(1);
; #pragma unroll
;             for (int kb = 0; kb < 4; ++kb)
; #pragma unroll
;                 for (int qb2 = 0; qb2 < 2; ++qb2) S[kb][qb2] = __builtin_amdgcn_mfma_f32_16x16x32_bf16(kf[kb][0], qr[qb2][0], CI, 0, 0, 0);
; #pragma unroll
;             for (int kb = 0; kb < 4; ++kb)
; #pragma unroll
;                 for (int qb2 = 0; qb2 < 2; ++qb2) S[kb][qb2] = __builtin_amdgcn_mfma_f32_16x16x32_bf16(kf[kb][1], qr[qb2][1], S[kb][qb2], 0, 0, 0);
;             __builtin_amdgcn_s_setprio(0);
;             if (!far_) {
;                 const int rbase = 64 * kt - (q0 + x) + 191 + 4 * g;
; #pragma unroll
;                 for (int kb = 0; kb < 4; ++kb)
; #pragma unroll
;                     for (int qb2 = 0; qb2 < 2; ++qb2)
; #pragma unroll
;                         for (int i = 0; i < 4; ++i) S[kb][qb2][i] += tbl[rbase + 16 * kb - 16 * qb2 + i];
; __global__ void __launch_bounds__(512, 2) fwd(Args a) {
;     ...
;                     if (tid_ == 0) MISC[16] = __hip_atomic_fetch_add(qh, 1u, __ATOMIC_RELAXED, __HIP_MEMORY_SCOPE_AGENT);
;                     __syncthreads();
;                     const int item = (int)MISC[16];
.LBB0_539:
	v_mov_b32_e32 v213, 1
	s_and_saveexec_b64 s[100:101], s[40:41]
	s_cbranch_execz .Lqpf_x
	v_mov_b32_e32 v212, 1
	global_atomic_add v212, v169, v212, s[34:35] sc0
.Lqpf_x:
	s_or_b64 exec, exec, s[100:101]
	s_cmp_lt_u32 s10, 2
	s_cbranch_scc1 .LBB0_543
	s_sub_i32 s12, s27, s11
	s_bitcmp1_b32 s11, 0
	s_cselect_b32 s11, 0x4800, 0
	v_add_u32_e32 v112, s11, v150
	ds_read_b128 v[84:87], v112
	ds_read_b128 v[88:91], v112 offset:64
	ds_read_b128 v[92:95], v112 offset:4608
	ds_read_b128 v[100:103], v112 offset:4672
	ds_read_b128 v[96:99], v112 offset:9216
	ds_read_b128 v[104:107], v112 offset:9280
	ds_read_b128 v[108:111], v112 offset:13824
	ds_read_b128 v[112:115], v112 offset:13888
	s_setprio 1
	s_waitcnt lgkmcnt(7)
	v_mfma_f32_16x16x32_bf16 v[116:119], v[84:87], v[72:75], v[64:67]
	s_cmp_gt_u32 s12, 2
	v_mfma_f32_16x16x32_bf16 v[84:87], v[84:87], v[80:83], v[64:67]
	s_waitcnt lgkmcnt(5)
	v_mfma_f32_16x16x32_bf16 v[120:123], v[92:95], v[72:75], v[64:67]
	v_mfma_f32_16x16x32_bf16 v[124:127], v[92:95], v[80:83], v[64:67]
	s_waitcnt lgkmcnt(3)
	v_mfma_f32_16x16x32_bf16 v[128:131], v[96:99], v[72:75], v[64:67]
	v_mfma_f32_16x16x32_bf16 v[134:137], v[96:99], v[80:83], v[64:67]
	s_waitcnt lgkmcnt(1)
	v_mfma_f32_16x16x32_bf16 v[148:151], v[108:111], v[72:75], v[64:67]
	v_mfma_f32_16x16x32_bf16 v[64:67], v[108:111], v[80:83], v[64:67]
	v_mfma_f32_16x16x32_bf16 v[96:99], v[88:91], v[68:71], v[116:119]
	v_mfma_f32_16x16x32_bf16 v[92:95], v[88:91], v[76:79], v[84:87]
	v_mfma_f32_16x16x32_bf16 v[88:91], v[100:103], v[68:71], v[120:123]
	v_mfma_f32_16x16x32_bf16 v[84:87], v[100:103], v[76:79], v[124:127]
	v_mfma_f32_16x16x32_bf16 v[80:83], v[104:107], v[68:71], v[128:131]
	v_mfma_f32_16x16x32_bf16 v[72:75], v[104:107], v[76:79], v[134:137]
	s_waitcnt lgkmcnt(0)
	v_mfma_f32_16x16x32_bf16 v[68:71], v[112:115], v[68:71], v[148:151]
	v_mfma_f32_16x16x32_bf16 v[64:67], v[112:115], v[76:79], v[64:67]
	s_setprio 0
	s_cbranch_scc1 .LBB0_542
	s_lshl_b32 s0, s0, 2
	v_or_b32_e32 v76, s1, v146
	s_add_i32 s0, s0, 0
	v_sub_u32_e32 v76, v144, v76
	s_addk_i32 s0, 0x100
	v_lshl_add_u32 v78, v76, 2, s0
	v_add_u32_e32 v100, 0x122fc, v78
	v_add_u32_e32 v76, 0x122bc, v78
	v_add_u32_e32 v78, 0x122c4, v78
	ds_read2_b32 v[76:77], v76 offset1:1
	ds_read2_b32 v[78:79], v78 offset1:1
	s_waitcnt lgkmcnt(1)
	v_pk_add_f32 v[92:93], v[92:93], v[76:77]
	s_waitcnt lgkmcnt(0)
	v_pk_add_f32 v[94:95], v[94:95], v[78:79]
	ds_read2_b32 v[76:77], v100 offset1:1
	ds_read2_b32 v[78:79], v100 offset0:2 offset1:3
	s_waitcnt lgkmcnt(1)
	v_pk_add_f32 v[96:97], v[96:97], v[76:77]
	s_waitcnt lgkmcnt(0)
	v_pk_add_f32 v[98:99], v[98:99], v[78:79]
	v_pk_add_f32 v[86:87], v[86:87], v[78:79]
	v_pk_add_f32 v[84:85], v[84:85], v[76:77]
	ds_read2_b32 v[76:77], v100 offset0:16 offset1:17
	ds_read2_b32 v[78:79], v100 offset0:18 offset1:19
	s_waitcnt lgkmcnt(1)
	v_pk_add_f32 v[88:89], v[88:89], v[76:77]
	s_waitcnt lgkmcnt(0)
	v_pk_add_f32 v[90:91], v[90:91], v[78:79]
	v_pk_add_f32 v[74:75], v[74:75], v[78:79]
	v_pk_add_f32 v[72:73], v[72:73], v[76:77]
	ds_read2_b32 v[76:77], v100 offset0:48 offset1:49
	ds_read2_b32 v[78:79], v100 offset0:50 offset1:51
	s_waitcnt lgkmcnt(1)
	v_pk_add_f32 v[68:69], v[68:69], v[76:77]
	s_waitcnt lgkmcnt(0)
	v_pk_add_f32 v[70:71], v[70:71], v[78:79]
	ds_read2_b32 v[76:77], v100 offset0:32 offset1:33
	ds_read2_b32 v[78:79], v100 offset0:34 offset1:35
	s_waitcnt lgkmcnt(1)
	v_pk_add_f32 v[80:81], v[80:81], v[76:77]
	s_waitcnt lgkmcnt(0)
	v_pk_add_f32 v[82:83], v[82:83], v[78:79]
	v_pk_add_f32 v[66:67], v[66:67], v[78:79]
	v_pk_add_f32 v[64:65], v[64:65], v[76:77]
